# combo2 plus: QK MFMA chains adjacent in attention phase A, K/V LDS-DMA pieces issued by waves 0-3 only, merge loop next-row loads un-serialised
# baseline (speedup 1.0000x reference)
_Z14fwd_megakernel6Params:
	s_load_dword s33, s[0:1], 0xd8
	s_load_dwordx4 s[28:31], s[0:1], 0xc0
	s_load_dwordx2 s[24:25], s[0:1], 0xd0
	v_and_b32_e32 v234, 0x3ff, v0
	v_readfirstlane_b32 s99, v0
	s_nop 3
	s_bfe_u32 s99, s99, 0x40006
	s_lshr_b32 s99, s99, 2
	s_mov_b64 s[100:101], 0x1000
	v_writelane_b32 v253, s2, 0
	s_add_u32 s2, s0, 0xd0
	s_addc_u32 s3, s1, 0
	v_cmp_gt_u32_e32 vcc, 2, v234
	s_and_saveexec_b64 s[4:5], vcc
	v_lshl_add_u32 v1, v234, 2, 0
	v_add_u32_e32 v1, 0x25f00, v1
	v_mov_b32_e32 v2, 0
	ds_write_b32 v1, v2
	s_or_b64 exec, exec, s[4:5]
	s_waitcnt lgkmcnt(0)
	s_barrier
	s_add_u32 s84, s30, 0x980000
	s_getreg_b32 s4, hwreg(HW_REG_XCC_ID, 0, 4)
	s_addc_u32 s85, s31, 0
	s_and_b32 s27, s4, 15
	v_cmp_eq_u32_e64 s[6:7], 0, v234
	s_mov_b64 s[4:5], exec
	s_nop 0
	v_writelane_b32 v253, s6, 1
	s_nop 1
	v_writelane_b32 v253, s7, 2
	s_and_b64 s[6:7], s[4:5], s[6:7]
	s_mov_b64 exec, s[6:7]
	s_cbranch_execz .LBB0_5
	s_mov_b64 s[6:7], exec
	v_mbcnt_lo_u32_b32 v1, s6, 0
	v_mbcnt_hi_u32_b32 v1, s7, v1
	v_cmp_eq_u32_e32 vcc, 0, v1
	s_and_b64 s[8:9], exec, vcc
	s_mov_b64 exec, s[8:9]
	s_cbranch_execz .LBB0_5
	s_lshl_b32 s8, s27, 8
	s_bcnt1_i32_b64 s6, s[6:7]
	v_mov_b32_e32 v1, s8
	v_mov_b32_e32 v2, s6
	global_atomic_add v1, v2, s[84:85] offset:1024

.LBB0_485:
	v_add_u32_e32 v190, s4, v203
	ds_read_b64_tr_b16 v[178:179], v190 offset:24576
	ds_read_b64_tr_b16 v[180:181], v190 offset:25088
	s_waitcnt lgkmcnt(9)
	v_mfma_f32_32x32x16_bf16 v[98:113], v[174:177], v[142:145], v[34:49]
	v_add_f32_e32 v82, v66, v67
	v_add_f32_e32 v82, v68, v82
	v_add_f32_e32 v82, v69, v82
	v_add_f32_e32 v82, v70, v82
	v_add_f32_e32 v82, v71, v82
	v_cvt_pk_bf16_f32 v138, v66, v67
	v_cvt_pk_bf16_f32 v139, v68, v69
	ds_read_b64_tr_b16 v[174:175], v190 offset:28672
	ds_read_b64_tr_b16 v[176:177], v190 offset:29184
	v_add_f32_e32 v66, v72, v82
	s_waitcnt lgkmcnt(10)
	v_mfma_f32_32x32x16_bf16 v[98:113], v[166:169], v[134:137], v[98:113]
	v_add_f32_e32 v66, v73, v66
	v_add_f32_e32 v66, v74, v66
	v_add_f32_e32 v114, v75, v66
	v_cvt_pk_bf16_f32 v140, v70, v71
	v_cvt_pk_bf16_f32 v141, v72, v73
	ds_read_b64_tr_b16 v[66:67], v190 offset:25600
	ds_read_b64_tr_b16 v[68:69], v190 offset:26112
	s_waitcnt lgkmcnt(11)
	v_mfma_f32_32x32x16_bf16 v[98:113], v[158:161], v[126:129], v[98:113]
	v_add_f32_e32 v70, v76, v114
	v_add_f32_e32 v70, v77, v70
	v_add_f32_e32 v70, v78, v70
	v_add_f32_e32 v114, v79, v70
	v_cvt_pk_bf16_f32 v130, v74, v75
	v_cvt_pk_bf16_f32 v131, v76, v77
	ds_read_b64_tr_b16 v[70:71], v190 offset:29696
	ds_read_b64_tr_b16 v[72:73], v190 offset:30208
	s_waitcnt lgkmcnt(12)
	v_mfma_f32_32x32x16_bf16 v[98:113], v[150:153], v[118:121], v[98:113]
	v_add_f32_e32 v74, v80, v114
	v_add_f32_e32 v74, v81, v74
	v_add_f32_e32 v74, v50, v74
	v_add_f32_e32 v114, v51, v74
	v_cvt_pk_bf16_f32 v132, v78, v79
	v_cvt_pk_bf16_f32 v133, v80, v81
	ds_read_b64_tr_b16 v[74:75], v190 offset:26624
	ds_read_b64_tr_b16 v[76:77], v190 offset:27136
	s_waitcnt lgkmcnt(13)
	v_mfma_f32_32x32x16_bf16 v[82:97], v[170:173], v[142:145], v[34:49]
	v_add_f32_e32 v78, v52, v114
	v_add_f32_e32 v78, v53, v78
	v_add_f32_e32 v78, v54, v78
	v_add_f32_e32 v78, v55, v78
	v_cvt_pk_bf16_f32 v122, v50, v51
	v_cvt_pk_bf16_f32 v123, v52, v53
	ds_read_b64_tr_b16 v[50:51], v190 offset:30720
	ds_read_b64_tr_b16 v[52:53], v190 offset:31232
	s_waitcnt lgkmcnt(14)
	v_mfma_f32_32x32x16_bf16 v[82:97], v[162:165], v[134:137], v[82:97]
	v_add_f32_e32 v78, v56, v78
	v_add_f32_e32 v78, v57, v78
	v_add_f32_e32 v78, v58, v78
	v_add_f32_e32 v78, v59, v78
	v_cvt_pk_bf16_f32 v124, v54, v55
	v_cvt_pk_bf16_f32 v125, v56, v57
	ds_read_b64_tr_b16 v[54:55], v190 offset:27648
	ds_read_b64_tr_b16 v[56:57], v190 offset:28160
	s_waitcnt lgkmcnt(14)
	v_mfma_f32_32x32x16_bf16 v[82:97], v[154:157], v[126:129], v[82:97]
	v_add_f32_e32 v78, v60, v78
	v_add_f32_e32 v78, v61, v78
	v_add_f32_e32 v78, v62, v78
	v_add_f32_e32 v78, v63, v78
	v_cvt_pk_bf16_f32 v114, v58, v59
	v_cvt_pk_bf16_f32 v115, v60, v61
	ds_read_b64_tr_b16 v[58:59], v190 offset:31744
	ds_read_b64_tr_b16 v[60:61], v190 offset:32256
	v_mfma_f32_32x32x16_bf16 v[82:97], v[146:149], v[118:121], v[82:97]
	v_add_f32_e32 v78, v64, v78
	v_add_f32_e32 v78, v65, v78
	v_add_f32_e32 v78, 0, v78
	v_cvt_pk_bf16_f32 v116, v62, v63
	v_cvt_pk_bf16_f32 v117, v64, v65
	s_cmp_lg_u32 s99, 0
	s_cbranch_scc1 .Ldsh_1y
	v_lshl_add_u64 v[62:63], v[188:189], 0, s[80:81]
	s_add_i32 s4, s11, s46
	s_mov_b32 s5, m0
	s_mov_b32 m0, s4
	s_nop 0
	global_load_lds_dwordx4 v[62:63], off
	s_mov_b32 m0, s5
	v_lshl_add_u64 v[214:215], v[62:63], 0, s[100:101]
	s_add_i32 s4, s4, 0x1000
	s_mov_b32 s5, m0
	s_mov_b32 m0, s4
	s_nop 0
	global_load_lds_dwordx4 v[214:215], off
	s_mov_b32 m0, s5
	v_lshl_add_u64 v[62:63], v[186:187], 0, s[80:81]
	s_add_i32 s4, s14, s47
	s_mov_b32 s5, m0
	s_mov_b32 m0, s4
	s_nop 0
	global_load_lds_dwordx4 v[62:63], off
	s_mov_b32 m0, s5
	v_lshl_add_u64 v[214:215], v[62:63], 0, s[100:101]
	s_add_i32 s4, s4, 0x1000
	s_mov_b32 s5, m0
	s_mov_b32 m0, s4
	s_nop 0
	global_load_lds_dwordx4 v[214:215], off
	s_mov_b32 m0, s5
	s_branch .Ldsh_1d
.Ldsh_1y:
	s_nop 5
.Ldsh_1d:
	v_max_f32_e32 v62, v99, v99
	v_max_f32_e32 v63, v98, v98
	v_max_f32_e32 v62, v63, v62
	v_max3_f32 v63, v100, v101, v83
	v_max3_f32 v62, v62, v82, v84
	v_max3_f32 v62, v62, v85, v102
	v_max3_f32 v63, v63, v104, v105
	v_max3_f32 v62, v62, v103, v86
	v_max3_f32 v63, v63, v88, v89
	v_max3_f32 v62, v62, v87, v106
	v_max3_f32 v63, v63, v108, v109
	v_max3_f32 v62, v62, v107, v90
	v_max3_f32 v63, v63, v92, v93
	v_max3_f32 v62, v62, v91, v110
	v_max3_f32 v63, v63, v112, v113
	v_max3_f32 v62, v62, v111, v94
	v_max3_f32 v63, v63, v96, v97
	v_max3_f32 v62, v62, v95, v63
	v_mov_b32_e32 v63, v62
	s_nop 1
	v_permlane32_swap_b32_e32 v62, v63
	v_max_f32_e32 v63, v63, v63
	v_max_f32_e32 v62, v62, v62
	v_max_f32_e32 v62, v62, v63
	v_cmp_lt_f32_e32 vcc, s93, v62
	s_cmp_lg_u64 vcc, 0
	v_add_f32_e32 v190, v205, v78
	s_cselect_b64 s[4:5], -1, 0
	s_cbranch_vccnz .LBB0_493
.LBB0_486:
	s_waitcnt lgkmcnt(14)
	v_mfma_f32_32x32x16_bf16 v[18:33], v[138:141], v[178:181], v[18:33]
	v_exp_f32_e32 v98, v98
	v_exp_f32_e32 v99, v99
	v_exp_f32_e32 v100, v100
	v_exp_f32_e32 v101, v101
	s_waitcnt lgkmcnt(12)
	v_mfma_f32_32x32x16_bf16 v[2:17], v[138:141], v[174:177], v[2:17]
	v_exp_f32_e32 v102, v102
	v_exp_f32_e32 v103, v103
	v_exp_f32_e32 v104, v104
	v_exp_f32_e32 v105, v105
	v_add_u32_e32 v78, s14, v202
	ds_read_b128 v[62:65], v78
	ds_read_b128 v[174:177], v78 offset:512
	s_waitcnt lgkmcnt(12)
	v_mfma_f32_32x32x16_bf16 v[18:33], v[130:133], v[66:69], v[18:33]
	v_exp_f32_e32 v106, v106
	v_exp_f32_e32 v107, v107
	v_exp_f32_e32 v108, v108
	v_exp_f32_e32 v109, v109
	ds_read_b128 v[178:181], v78 offset:2048
	ds_read_b128 v[170:173], v78 offset:2560
	s_waitcnt lgkmcnt(12)
	v_mfma_f32_32x32x16_bf16 v[2:17], v[130:133], v[70:73], v[2:17]
	v_exp_f32_e32 v110, v110
	v_exp_f32_e32 v111, v111
	v_exp_f32_e32 v112, v112
	v_exp_f32_e32 v113, v113
	ds_read_b128 v[166:169], v78 offset:4096
	ds_read_b128 v[162:165], v78 offset:4608
	s_waitcnt lgkmcnt(12)
	v_mfma_f32_32x32x16_bf16 v[18:33], v[122:125], v[74:77], v[18:33]
	v_exp_f32_e32 v82, v82
	v_exp_f32_e32 v83, v83
	v_exp_f32_e32 v84, v84
	v_exp_f32_e32 v85, v85
	ds_read_b128 v[158:161], v78 offset:6144
	ds_read_b128 v[154:157], v78 offset:6656
	s_waitcnt lgkmcnt(12)
	v_mfma_f32_32x32x16_bf16 v[2:17], v[122:125], v[50:53], v[2:17]
	v_exp_f32_e32 v86, v86
	v_exp_f32_e32 v87, v87
	v_exp_f32_e32 v88, v88
	v_exp_f32_e32 v89, v89
	s_waitcnt lgkmcnt(10)
	v_mfma_f32_32x32x16_bf16 v[18:33], v[114:117], v[54:57], v[18:33]
	v_exp_f32_e32 v90, v90
	v_exp_f32_e32 v91, v91
	v_exp_f32_e32 v92, v92
	v_exp_f32_e32 v93, v93
	s_waitcnt lgkmcnt(8)
	v_mfma_f32_32x32x16_bf16 v[2:17], v[114:117], v[58:61], v[2:17]
	v_exp_f32_e32 v94, v94
	v_exp_f32_e32 v95, v95
	v_exp_f32_e32 v96, v96
	v_exp_f32_e32 v97, v97
	s_cmp_lg_u32 s99, 0
	s_cbranch_scc1 .Ldsh_c1y
	s_waitcnt vmcnt(4) lgkmcnt(0)
	s_branch .Ldsh_c1b
.Ldsh_c1y:
	s_waitcnt vmcnt(0) lgkmcnt(0)
.Ldsh_c1b:
	s_barrier
	s_andn2_b64 vcc, exec, s[4:5]
	v_add_u32_e32 v191, s18, v204
	s_cbranch_vccnz .LBB0_488
	s_waitcnt lgkmcnt(0)
	ds_read_b128 v[50:53], v191 offset:49248
	ds_read_b128 v[54:57], v191 offset:49216
	ds_read_b128 v[58:61], v191 offset:49184
	ds_read_b128 v[66:69], v191 offset:49152
	s_waitcnt lgkmcnt(3)
	v_pk_mul_f32 v[30:31], v[30:31], v[50:51]
	s_waitcnt lgkmcnt(2)
	v_pk_mul_f32 v[26:27], v[26:27], v[54:55]
	s_waitcnt lgkmcnt(1)
	v_pk_mul_f32 v[22:23], v[22:23], v[58:59]
	v_pk_mul_f32 v[32:33], v[32:33], v[52:53]
	v_pk_mul_f32 v[28:29], v[28:29], v[56:57]
	v_pk_mul_f32 v[24:25], v[24:25], v[60:61]
	s_waitcnt lgkmcnt(0)
	v_pk_mul_f32 v[20:21], v[20:21], v[68:69]
	v_pk_mul_f32 v[18:19], v[18:19], v[66:67]
	v_pk_mul_f32 v[14:15], v[14:15], v[50:51]
	v_pk_mul_f32 v[10:11], v[10:11], v[54:55]
	v_pk_mul_f32 v[6:7], v[6:7], v[58:59]
	v_pk_mul_f32 v[16:17], v[16:17], v[52:53]
	v_pk_mul_f32 v[12:13], v[12:13], v[56:57]
	v_pk_mul_f32 v[8:9], v[8:9], v[60:61]
	v_pk_mul_f32 v[4:5], v[4:5], v[68:69]
	v_pk_mul_f32 v[2:3], v[2:3], v[66:67]
.LBB0_488:
	s_add_i32 s4, s14, 0x2000
	s_cmpk_lg_i32 s14, 0x4000
	s_cselect_b32 s50, s4, 0
	v_add_u32_e32 v192, s11, v203
	ds_read_b64_tr_b16 v[150:151], v192 offset:24576
	ds_read_b64_tr_b16 v[152:153], v192 offset:25088
	s_waitcnt lgkmcnt(9)
	v_mfma_f32_32x32x16_bf16 v[66:81], v[62:65], v[142:145], v[34:49]
	v_add_f32_e32 v50, v98, v99
	v_add_f32_e32 v50, v100, v50
	v_add_f32_e32 v50, v101, v50
	v_add_f32_e32 v50, v102, v50
	v_add_f32_e32 v50, v103, v50
	v_cvt_pk_bf16_f32 v138, v98, v99
	v_cvt_pk_bf16_f32 v139, v100, v101
	ds_read_b64_tr_b16 v[146:147], v192 offset:28672
	ds_read_b64_tr_b16 v[148:149], v192 offset:29184
	v_add_f32_e32 v50, v104, v50
	v_add_f32_e32 v50, v105, v50
	v_add_f32_e32 v50, v106, v50
	v_add_f32_e32 v114, v107, v50
	s_waitcnt lgkmcnt(10)
	v_mfma_f32_32x32x16_bf16 v[66:81], v[178:181], v[134:137], v[66:81]
	v_cvt_pk_bf16_f32 v140, v102, v103
	v_cvt_pk_bf16_f32 v141, v104, v105
	ds_read_b64_tr_b16 v[98:99], v192 offset:25600
	ds_read_b64_tr_b16 v[100:101], v192 offset:26112
	s_waitcnt lgkmcnt(11)
	v_mfma_f32_32x32x16_bf16 v[66:81], v[166:169], v[126:129], v[66:81]
	v_add_f32_e32 v102, v108, v114
	v_add_f32_e32 v102, v109, v102
	v_add_f32_e32 v102, v110, v102
	v_add_f32_e32 v114, v111, v102
	v_cvt_pk_bf16_f32 v130, v106, v107
	v_cvt_pk_bf16_f32 v131, v108, v109
	ds_read_b64_tr_b16 v[102:103], v192 offset:29696
	ds_read_b64_tr_b16 v[104:105], v192 offset:30208
	s_waitcnt lgkmcnt(12)
	v_mfma_f32_32x32x16_bf16 v[66:81], v[158:161], v[118:121], v[66:81]
	v_add_f32_e32 v106, v112, v114
	v_add_f32_e32 v106, v113, v106
	v_add_f32_e32 v106, v82, v106
	v_add_f32_e32 v114, v83, v106
	v_cvt_pk_bf16_f32 v132, v110, v111
	v_cvt_pk_bf16_f32 v133, v112, v113
	ds_read_b64_tr_b16 v[106:107], v192 offset:26624
	ds_read_b64_tr_b16 v[108:109], v192 offset:27136
	s_waitcnt lgkmcnt(13)
	v_mfma_f32_32x32x16_bf16 v[50:65], v[174:177], v[142:145], v[34:49]
	v_add_f32_e32 v110, v84, v114
	v_add_f32_e32 v110, v85, v110
	v_add_f32_e32 v110, v86, v110
	v_add_f32_e32 v110, v87, v110
	v_cvt_pk_bf16_f32 v122, v82, v83
	v_cvt_pk_bf16_f32 v123, v84, v85
	ds_read_b64_tr_b16 v[82:83], v192 offset:30720
	ds_read_b64_tr_b16 v[84:85], v192 offset:31232
	s_waitcnt lgkmcnt(14)
	v_mfma_f32_32x32x16_bf16 v[50:65], v[170:173], v[134:137], v[50:65]
	v_add_f32_e32 v110, v88, v110
	v_add_f32_e32 v110, v89, v110
	v_add_f32_e32 v110, v90, v110
	v_add_f32_e32 v110, v91, v110
	v_cvt_pk_bf16_f32 v124, v86, v87
	v_cvt_pk_bf16_f32 v125, v88, v89
	ds_read_b64_tr_b16 v[86:87], v192 offset:27648
	ds_read_b64_tr_b16 v[88:89], v192 offset:28160
	s_waitcnt lgkmcnt(14)
	v_mfma_f32_32x32x16_bf16 v[50:65], v[162:165], v[126:129], v[50:65]
	v_add_f32_e32 v110, v92, v110
	v_add_f32_e32 v110, v93, v110
	v_add_f32_e32 v110, v94, v110
	v_add_f32_e32 v110, v95, v110
	v_cvt_pk_bf16_f32 v114, v90, v91
	v_cvt_pk_bf16_f32 v115, v92, v93
	ds_read_b64_tr_b16 v[90:91], v192 offset:31744
	ds_read_b64_tr_b16 v[92:93], v192 offset:32256
	v_mfma_f32_32x32x16_bf16 v[50:65], v[154:157], v[118:121], v[50:65]
	v_add_f32_e32 v110, v96, v110
	v_add_f32_e32 v110, v97, v110
	v_add_f32_e32 v110, 0, v110
	v_cvt_pk_bf16_f32 v116, v94, v95
	v_cvt_pk_bf16_f32 v117, v96, v97
	v_max_f32_e32 v94, v67, v67
	v_max_f32_e32 v95, v66, v66
	v_max_f32_e32 v94, v95, v94
	s_nop 3
	v_max3_f32 v95, v68, v69, v51
	v_max3_f32 v94, v94, v50, v52
	v_max3_f32 v94, v94, v53, v70
	v_max3_f32 v95, v95, v72, v73
	v_max3_f32 v94, v94, v71, v54
	v_max3_f32 v95, v95, v56, v57
	v_max3_f32 v94, v94, v55, v74
	v_max3_f32 v95, v95, v76, v77
	v_max3_f32 v94, v94, v75, v58
	v_max3_f32 v95, v95, v60, v61
	v_max3_f32 v94, v94, v59, v78
	v_max3_f32 v95, v95, v80, v81
	v_max3_f32 v94, v94, v79, v62
	v_max3_f32 v95, v95, v64, v65
	v_max3_f32 v94, v94, v63, v95
	v_mov_b32_e32 v95, v94
	s_nop 1
	v_permlane32_swap_b32_e32 v94, v95
	v_max_f32_e32 v95, v95, v95
	v_max_f32_e32 v94, v94, v94
	s_cmp_lg_u32 s99, 0
	s_cbranch_scc1 .Ldsh_2k
	s_add_i32 s4, s14, s46
	s_mov_b32 s5, m0
	s_mov_b32 m0, s4
	s_nop 0
	global_load_lds_dwordx4 v[188:189], off
	s_mov_b32 m0, s5
	v_lshl_add_u64 v[214:215], v[188:189], 0, s[100:101]
	s_add_i32 s4, s4, 0x1000
	s_mov_b32 s5, m0
	s_mov_b32 m0, s4
	s_nop 0
	global_load_lds_dwordx4 v[214:215], off
	s_mov_b32 m0, s5
.Ldsh_2k:
	v_max_f32_e32 v94, v94, v95
	s_cmp_lg_u32 s99, 0
	s_cbranch_scc1 .Ldsh_2v
	s_add_i32 s4, s50, s47
	s_mov_b32 s5, m0
	s_mov_b32 m0, s4
	s_nop 0
	global_load_lds_dwordx4 v[186:187], off
	s_mov_b32 m0, s5
	v_lshl_add_u64 v[214:215], v[186:187], 0, s[100:101]
	s_add_i32 s4, s4, 0x1000
	s_mov_b32 s5, m0
	s_mov_b32 m0, s4
	s_nop 0
	global_load_lds_dwordx4 v[214:215], off
	s_mov_b32 m0, s5
.Ldsh_2v:
	v_cmp_lt_f32_e32 vcc, s93, v94
	s_cmp_lg_u64 vcc, 0
	v_add_f32_e32 v205, v190, v110
	s_cselect_b64 s[4:5], -1, 0
	s_cbranch_vccnz .LBB0_496
.LBB0_489:
	s_waitcnt lgkmcnt(14)
	v_mfma_f32_32x32x16_bf16 v[18:33], v[138:141], v[150:153], v[18:33]
	v_exp_f32_e32 v66, v66
	v_exp_f32_e32 v67, v67
	v_exp_f32_e32 v68, v68
	v_exp_f32_e32 v69, v69
	s_waitcnt lgkmcnt(12)
	v_mfma_f32_32x32x16_bf16 v[2:17], v[138:141], v[146:149], v[2:17]
	v_exp_f32_e32 v70, v70
	v_exp_f32_e32 v71, v71
	v_exp_f32_e32 v72, v72
	v_exp_f32_e32 v73, v73
	v_add_u32_e32 v94, s50, v202
	ds_read_b128 v[174:177], v94
	ds_read_b128 v[170:173], v94 offset:512
	s_waitcnt lgkmcnt(12)
	v_mfma_f32_32x32x16_bf16 v[18:33], v[130:133], v[98:101], v[18:33]
	v_exp_f32_e32 v74, v74
	v_exp_f32_e32 v75, v75
	v_exp_f32_e32 v76, v76
	v_exp_f32_e32 v77, v77
	ds_read_b128 v[166:169], v94 offset:2048
	ds_read_b128 v[162:165], v94 offset:2560
	s_waitcnt lgkmcnt(12)
	v_mfma_f32_32x32x16_bf16 v[2:17], v[130:133], v[102:105], v[2:17]
	v_exp_f32_e32 v78, v78
	v_exp_f32_e32 v79, v79
	v_exp_f32_e32 v80, v80
	v_exp_f32_e32 v81, v81
	ds_read_b128 v[158:161], v94 offset:4096
	ds_read_b128 v[154:157], v94 offset:4608
	s_waitcnt lgkmcnt(12)
	v_mfma_f32_32x32x16_bf16 v[18:33], v[122:125], v[106:109], v[18:33]
	v_exp_f32_e32 v50, v50
	v_exp_f32_e32 v51, v51
	v_exp_f32_e32 v52, v52
	v_exp_f32_e32 v53, v53
	ds_read_b128 v[150:153], v94 offset:6144
	ds_read_b128 v[146:149], v94 offset:6656
	s_waitcnt lgkmcnt(12)
	v_mfma_f32_32x32x16_bf16 v[2:17], v[122:125], v[82:85], v[2:17]
	v_exp_f32_e32 v54, v54
	v_exp_f32_e32 v55, v55
	v_exp_f32_e32 v56, v56
	v_exp_f32_e32 v57, v57
	s_waitcnt lgkmcnt(10)
	v_mfma_f32_32x32x16_bf16 v[18:33], v[114:117], v[86:89], v[18:33]
	v_exp_f32_e32 v58, v58
	v_exp_f32_e32 v59, v59
	v_exp_f32_e32 v60, v60
	v_exp_f32_e32 v61, v61
	s_waitcnt lgkmcnt(8)
	v_mfma_f32_32x32x16_bf16 v[2:17], v[114:117], v[90:93], v[2:17]
	v_exp_f32_e32 v62, v62
	v_exp_f32_e32 v63, v63
	v_exp_f32_e32 v64, v64
	v_exp_f32_e32 v65, v65
	s_cmp_lg_u32 s99, 0
	s_cbranch_scc1 .Ldsh_c2y
	s_waitcnt vmcnt(4) lgkmcnt(0)
	s_branch .Ldsh_c2b

.Ldsh_c2b:
	s_barrier
	s_andn2_b64 vcc, exec, s[4:5]
	s_cbranch_vccnz .LBB0_491
	s_waitcnt lgkmcnt(0)
	ds_read_b128 v[82:85], v191 offset:49248
	ds_read_b128 v[86:89], v191 offset:49216
	ds_read_b128 v[90:93], v191 offset:49152
	ds_read_b128 v[94:97], v191 offset:49184
	s_waitcnt lgkmcnt(3)
	v_pk_mul_f32 v[32:33], v[32:33], v[84:85]
	v_pk_mul_f32 v[30:31], v[30:31], v[82:83]
	s_waitcnt lgkmcnt(2)
	v_pk_mul_f32 v[28:29], v[28:29], v[88:89]
	v_pk_mul_f32 v[26:27], v[26:27], v[86:87]
	s_waitcnt lgkmcnt(0)
	v_pk_mul_f32 v[24:25], v[24:25], v[96:97]
	v_pk_mul_f32 v[22:23], v[22:23], v[94:95]
	v_pk_mul_f32 v[20:21], v[20:21], v[92:93]
	v_pk_mul_f32 v[18:19], v[18:19], v[90:91]
	v_pk_mul_f32 v[16:17], v[16:17], v[84:85]
	v_pk_mul_f32 v[14:15], v[14:15], v[82:83]
	v_pk_mul_f32 v[12:13], v[12:13], v[88:89]
	v_pk_mul_f32 v[10:11], v[10:11], v[86:87]
	v_pk_mul_f32 v[8:9], v[8:9], v[96:97]
	v_pk_mul_f32 v[6:7], v[6:7], v[94:95]
	v_pk_mul_f32 v[4:5], v[4:5], v[92:93]
	v_pk_mul_f32 v[2:3], v[2:3], v[90:91]

.LBB0_621:
	v_lshl_add_u64 v[46:47], s[14:15], 0, v[70:71]
	v_add_co_u32_e32 v40, vcc, 0x2ec00000, v46
	s_cmp_lg_u32 s98, 0
	s_cbranch_scc1 .Lmg_w2
	s_waitcnt vmcnt(0)
	s_branch .Lmg_w

.Lmg_w:
	v_mov_b32_e32 v210, v36
	v_addc_co_u32_e32 v41, vcc, 0, v47, vcc
	v_add_co_u32_e32 v48, vcc, 0x32e00000, v46
	global_load_dwordx4 v[40:43], v[40:41], off
	s_nop 0
	v_addc_co_u32_e32 v49, vcc, 0, v47, vcc
	global_load_dwordx4 v[48:51], v[48:49], off
	v_add_co_u32_e32 v82, vcc, 0x26800000, v44
	s_mov_b32 s4, 0xf800000
	s_nop 0
	v_addc_co_u32_e32 v83, vcc, 0, v45, vcc
	global_load_dwordx2 v[84:85], v[82:83], off
	v_add_co_u32_e32 v44, vcc, 0x28900000, v44
	v_lshl_add_u64 v[64:65], v[64:65], 0, s[10:11]
	s_nop 0
	v_addc_co_u32_e32 v45, vcc, 0, v45, vcc
	global_load_dwordx2 v[88:89], v[44:45], off
	v_add_co_u32_e32 v44, vcc, 0x37000000, v46
	v_lshl_add_u64 v[72:73], v[72:73], 0, s[10:11]
	s_nop 0
	v_addc_co_u32_e32 v45, vcc, 0, v47, vcc
	global_load_dwordx4 v[44:47], v[44:45], off
	s_cmp_lg_u32 s98, 0
	s_cbranch_scc0 .Lmg_nc
	s_waitcnt vmcnt(5)
	v_lshlrev_b32_e32 v248, 16, v214
	v_and_b32_e32 v249, 0xffff0000, v214
	v_lshlrev_b32_e32 v250, 16, v215
	v_and_b32_e32 v251, 0xffff0000, v215
	v_lshlrev_b32_e32 v246, 16, v216
	v_and_b32_e32 v247, 0xffff0000, v216
	v_lshlrev_b32_e32 v216, 16, v217
	v_and_b32_e32 v217, 0xffff0000, v217
	v_pk_mul_f32 v[74:75], v[250:251], v[216:217]
	v_pk_mul_f32 v[76:77], v[248:249], v[246:247]
	v_mov_b32_e32 v81, v74
	v_mov_b32_e32 v79, v76

.LBB0_626:
	s_mov_b32 s98, 0
	s_add_i32 s0, s4, 1
	v_mov_b32_e32 v79, 0
	s_cmp_eq_u32 s0, s5
	v_mov_b32_e32 v77, 0
	v_mov_b32_e32 v81, 0
	v_mov_b32_e32 v75, 0
	s_cbranch_scc1 .LBB0_621
	v_lshl_add_u64 v[246:247], s[14:15], 0, v[72:73]
	v_add_co_u32_e32 v214, vcc, 0x2aa00000, v246
	s_nop 1
	v_addc_co_u32_e32 v215, vcc, 0, v247, vcc
	v_add_co_u32_e32 v246, vcc, 0x2cb00000, v246
	global_load_dwordx2 v[214:215], v[214:215], off
	s_nop 0
	v_addc_co_u32_e32 v247, vcc, 0, v247, vcc
	global_load_dwordx2 v[216:217], v[246:247], off
	s_mov_b32 s98, 1
	s_branch .LBB0_621
